# in-projection epilogue: norm gain vectors loaded before the sum-of-squares stage (global loads into free fragment registers) instead of exposed flat loads in stage 2
# speedup vs baseline: 1.0067x; 1.0002x over previous
;     __device__ __forceinline__ void operator()(const f32x4 (&acc)[2][2][4][2], const Unit& u, int wr, int wc, int fr, int fq) const {
;     ...
;         for (int bj = 0; bj < 2; ++bj) {
;             const int c = u.pn * BM + bj * HALF + (wc >> 1) * 64;
;             gp[bj] = nullptr; sc[bj] = 1.0f;
;             if (c < 512) { gp[bj] = qga; sc[bj] = qs; } else if (c < 1024) gp[bj] = qga + 64;
;             else if (c >= BQ && c < BQ + 1536) { gp[bj] = qgb; sc[bj] = qs; } else if (c >= BKK && c < BKK + 1536) gp[bj] = qgb + 64;
;             else if (c >= DQ && c < DQ + 512) { gp[bj] = qgd; sc[bj] = qs; } else if (c >= DK && c < DK + 128) gp[bj] = qgd + 64;
;         }
;     ...
;         for (int bj = 0; bj < 2; ++bj) {
;             f32x4 g0 = (f32x4){1.f, 1.f, 1.f, 1.f}, g1 = g0;
;             if (gp[bj]) { const float* g = gp[bj] + (wc & 1) * 32 + fq * 8; g0 = *(const f32x4*)g * sc[bj]; g1 = *(const f32x4*)(g + 4) * sc[bj]; }
.LBB0_853:
	s_or_b64 vcc, s[58:59], s[54:55]
	s_cmp_eq_u64 vcc, 0
	s_cbranch_scc1 .Lmy_norm_skip
	v_lshlrev_b32_e32 v178, 2, v138
	v_mov_b32_e32 v179, 0
	s_lshl_b32 s21, s63, 2
	s_cmp_eq_u64 s[58:59], 0
	s_cbranch_scc1 .Lmy_g0_done
	s_add_u32 s22, s58, s21
	s_addc_u32 s23, s59, 0
	s_nop 0
	v_lshl_add_u64 v[180:181], s[22:23], 0, v[178:179]
	global_load_dwordx4 v[162:165], v[180:181], off
	global_load_dwordx4 v[166:169], v[180:181], off offset:16
.Lmy_g0_done:
	s_cmp_eq_u64 s[54:55], 0
	s_cbranch_scc1 .Lmy_g1_done
	s_add_u32 s22, s54, s21
	s_addc_u32 s23, s55, 0
	s_nop 0
	v_lshl_add_u64 v[182:183], s[22:23], 0, v[178:179]
	global_load_dwordx4 v[170:173], v[182:183], off
	global_load_dwordx4 v[174:177], v[182:183], off offset:16

;     __device__ __forceinline__ void operator()(const f32x4 (&acc)[2][2][4][2], const Unit& u, int wr, int wc, int fr, int fq) const {
;     ...
;         asm volatile("s_waitcnt lgkmcnt(0)" ::: "memory"); __builtin_amdgcn_s_barrier(); asm volatile("" ::: "memory");
; #pragma unroll
;         for (int bj = 0; bj < 2; ++bj) {
;             f32x4 g0 = (f32x4){1.f, 1.f, 1.f, 1.f}, g1 = g0;
;             if (gp[bj]) { const float* g = gp[bj] + (wc & 1) * 32 + fq * 8; g0 = *(const f32x4*)g * sc[bj]; g1 = *(const f32x4*)(g + 4) * sc[bj]; }
.Lmy_norm_skip:
	s_waitcnt lgkmcnt(0)
	s_barrier
	s_cmp_lg_u64 s[58:59], 0
	s_cselect_b64 s[60:61], -1, 0
	s_cmp_eq_u64 s[58:59], 0
	v_lshlrev_b32_e32 v0, 2, v138
	s_cbranch_scc1 .LBB0_922
	s_waitcnt vmcnt(0) lgkmcnt(0)
	v_pk_mul_f32 v[144:145], s[56:57], v[164:165] op_sel_hi:[0,1]
	v_pk_mul_f32 v[148:149], s[56:57], v[162:163] op_sel_hi:[0,1]
	v_pk_mul_f32 v[146:147], s[56:57], v[168:169] op_sel_hi:[0,1]
	v_pk_mul_f32 v[150:151], s[56:57], v[166:167] op_sel_hi:[0,1]
	v_cndmask_b32_e64 v152, 0, 1, s[60:61]
	v_cmp_ne_u32_e64 s[40:41], 1, v152
	s_andn2_b64 vcc, exec, s[60:61]
	s_cbranch_vccnz .LBB0_888

; #define LAS __attribute__((address_space(3)))
; __device__ __forceinline__ unsigned pk2(float lo, float hi) { unsigned r; asm volatile("v_cvt_pk_bf16_f32 %0, %1, %2" : "=v"(r) : "v"(lo), "v"(hi)); return r; }
;     __device__ __forceinline__ void operator()(const f32x4 (&acc)[2][2][4][2], const Unit& u, int wr, int wc, int fr, int fq) const {
;     ...
;         for (int bj = 0; bj < 2; ++bj) {
;             f32x4 g0 = (f32x4){1.f, 1.f, 1.f, 1.f}, g1 = g0;
;             if (gp[bj]) { const float* g = gp[bj] + (wc & 1) * 32 + fq * 8; g0 = *(const f32x4*)g * sc[bj]; g1 = *(const f32x4*)(g + 4) * sc[bj]; }
; #pragma unroll
;             for (int ai = 0; ai < 2; ++ai)
; #pragma unroll
;                 for (int m = 0; m < 4; ++m) {
;                     f32x4 v0 = acc[ai][bj][m][0], v1 = acc[ai][bj][m][1];
;                     if (gp[bj]) {
;                         const float tot = *(const LAS float*)(Pb + pown + ((ai * 4 + m) * 2 + bj) * 64) + *(const LAS float*)(Pb + ppar + ((ai * 4 + m) * 2 + bj) * 64);
;                         const float rs = rsqrtf(tot * (1.0f / 64.0f) + 1e-6f);
; #pragma unroll
;                         for (int e = 0; e < 4; ++e) { v0[e] = v0[e] * rs * g0[e]; v1[e] = v1[e] * rs * g1[e]; }
;                     }
;                     u32x4 w; w.x = pk2(v0[0], v0[1]); w.y = pk2(v0[2], v0[3]); w.z = pk2(v1[0], v1[1]); w.w = pk2(v1[2], v1[3]);
;                     *(u32x4*)(O + (size_t)(row0 + ai * HALF + m * 16) * NP1 + col0 + bj * HALF) = w;
.LBB0_902:
	v_cvt_pk_bf16_f32 v70, v70, v71
	v_cvt_pk_bf16_f32 v71, v72, v73
	v_cvt_pk_bf16_f32 v72, v66, v67
	s_nop 0
	v_cvt_pk_bf16_f32 v73, v68, v69
	v_add_u32_e32 v68, 0xb0, v161
	v_mov_b64_e32 v[66:67], s[34:35]
	v_mad_i64_i32 v[66:67], s[20:21], v68, s4, v[66:67]
	v_lshl_add_u64 v[66:67], v[152:153], 1, v[66:67]
	global_store_dwordx4 v[66:67], v[70:73], off
	s_cmp_lg_u64 s[54:55], 0
	s_cselect_b64 s[50:51], -1, 0
	s_cmp_eq_u64 s[54:55], 0
	s_cbranch_scc1 .LBB0_923
	s_waitcnt vmcnt(8)
	v_pk_mul_f32 v[68:69], s[52:53], v[172:173] op_sel_hi:[0,1]
	v_pk_mul_f32 v[72:73], s[52:53], v[170:171] op_sel_hi:[0,1]
	v_pk_mul_f32 v[70:71], s[52:53], v[176:177] op_sel_hi:[0,1]
	v_pk_mul_f32 v[76:77], s[52:53], v[174:175] op_sel_hi:[0,1]
	v_cndmask_b32_e64 v0, 0, 1, s[50:51]
	v_cmp_ne_u32_e64 s[40:41], 1, v0
	s_andn2_b64 vcc, exec, s[50:51]
	s_cbranch_vccnz .LBB0_905
